# grid barrier: non-last XCD leaders poll the TOP arrival counter against its target instead of the TOPGEN word (one cross-XCD hop less)
# speedup vs baseline: 1.0183x; 1.0051x over previous
; __device__ __forceinline__ unsigned xb_ld(unsigned* p)              { return __hip_atomic_load(p, __ATOMIC_RELAXED, __HIP_MEMORY_SCOPE_AGENT); }
; __device__ __forceinline__ unsigned xb_add(unsigned* p, unsigned v) { return __hip_atomic_fetch_add(p, v, __ATOMIC_RELAXED, __HIP_MEMORY_SCOPE_AGENT); }
; #define XB_SPIN(cond, bar) do { unsigned _sp = 0; while (cond) { __builtin_amdgcn_s_sleep(1); \
;     if ((++_sp & 255u) == 0u) { if (xb_ld(&(bar)[XB_TMO])) break; if (_sp > XB_SPIN_CAP) { atomicAdd(&(bar)[XB_TMO], 1u); break; } } } } while (0)
; __device__ __forceinline__ void xcd_barrier(const XcdBarrier& b) {
;     ...
;             const unsigned og = xb_add(&bar[XB_TOP], 1u);
;             const unsigned tg = og / nx;
;             if (og + 1u == (tg + 1u) * nx) xb_add(&bar[XB_TOPGEN], 1u);
;             else XB_SPIN(xb_ld(&bar[XB_TOPGEN]) == tg, bar);
.LBB0_112:
	s_or_b64 exec, exec, s[12:13]
	v_cvt_f32_u32_e32 v3, v0
	s_waitcnt vmcnt(0)
	v_readfirstlane_b32 s10, v2
	s_add_u32 s12, s92, 0x83500
	s_addc_u32 s13, s93, 0
	v_rcp_iflag_f32_e32 v3, v3
	v_add_u32_e32 v1, s10, v1
	v_add_u32_e32 v4, 1, v1
	s_mov_b64 s[14:15], -1
	v_mul_f32_e32 v2, 0x4f7ffffe, v3
	v_cvt_u32_f32_e32 v2, v2
	v_sub_u32_e32 v3, 0, v0
	v_mul_lo_u32 v3, v3, v2
	v_mul_hi_u32 v3, v2, v3
	v_add_u32_e32 v2, v2, v3
	v_mul_hi_u32 v2, v1, v2
	v_mul_lo_u32 v3, v2, v0
	v_sub_u32_e32 v1, v1, v3
	v_add_u32_e32 v5, 1, v2
	v_cmp_ge_u32_e32 vcc, v1, v0
	v_sub_u32_e32 v3, v1, v0
	s_nop 0
	v_cndmask_b32_e32 v2, v2, v5, vcc
	v_cndmask_b32_e32 v1, v1, v3, vcc
	v_add_u32_e32 v3, 1, v2
	v_cmp_ge_u32_e32 vcc, v1, v0
	s_nop 1
	v_cndmask_b32_e32 v2, v2, v3, vcc
	v_mul_lo_u32 v1, v0, v2
	v_add_u32_e32 v0, v1, v0
	v_mov_b32_e32 v5, v0
	v_cmp_ne_u32_e32 vcc, v4, v0
	v_mov_b64_e32 v[0:1], s[12:13]
	s_and_saveexec_b64 s[10:11], vcc
	s_cbranch_execz .LBB0_124
	v_mov_b32_e32 v0, 0
	global_load_dword v1, v0, s[12:13] offset:-256 sc1
	s_mov_b64 s[18:19], 0
	s_waitcnt vmcnt(0)
	v_cmp_lt_u32_e32 vcc, v1, v5
	s_and_saveexec_b64 s[16:17], vcc
	s_cbranch_execz .LBB0_123
	s_add_u32 s14, s92, 0x80200
	s_addc_u32 s15, s93, 0
	s_mov_b32 s28, 1
	s_branch .LBB0_116

; __device__ __forceinline__ unsigned xb_ld(unsigned* p)              { return __hip_atomic_load(p, __ATOMIC_RELAXED, __HIP_MEMORY_SCOPE_AGENT); }
; __device__ __forceinline__ unsigned xb_add(unsigned* p, unsigned v) { return __hip_atomic_fetch_add(p, v, __ATOMIC_RELAXED, __HIP_MEMORY_SCOPE_AGENT); }
; #define XB_SPIN(cond, bar) do { unsigned _sp = 0; while (cond) { __builtin_amdgcn_s_sleep(1); \
;     if ((++_sp & 255u) == 0u) { if (xb_ld(&(bar)[XB_TMO])) break; if (_sp > XB_SPIN_CAP) { atomicAdd(&(bar)[XB_TMO], 1u); break; } } } } while (0)
; __device__ __forceinline__ void xcd_barrier(const XcdBarrier& b) {
;     ...
;             const unsigned og = xb_add(&bar[XB_TOP], 1u);
;             const unsigned tg = og / nx;
;             if (og + 1u == (tg + 1u) * nx) xb_add(&bar[XB_TOPGEN], 1u);
;             else XB_SPIN(xb_ld(&bar[XB_TOPGEN]) == tg, bar);
.LBB0_120:
	global_load_dword v1, v0, s[12:13] offset:-256 sc1
	s_add_i32 s28, s28, 1
	s_mov_b64 s[22:23], -1
	s_waitcnt vmcnt(0)
	v_cmp_ge_u32_e32 vcc, v1, v5
	s_orn2_b64 s[26:27], vcc, exec
	s_branch .LBB0_115
